# grid barrier: early inv + single pre-clean wbl2 by 5th-from-last local arriver (K=4)
# baseline (speedup 1.0000x reference)
.LBB0_141:
	s_or_b64 exec, exec, s[8:9]
	v_cvt_f32_u32_e32 v4, v2
	s_waitcnt vmcnt(0)
	buffer_inv sc1
	v_readfirstlane_b32 s6, v3
	v_sub_u32_e32 v3, 0, v2
	v_rcp_iflag_f32_e32 v4, v4
	v_add_u32_e32 v5, s6, v1
	v_mul_f32_e32 v4, 0x4f7ffffe, v4
	v_cvt_u32_f32_e32 v4, v4
	v_mul_lo_u32 v1, v3, v4
	v_mul_hi_u32 v1, v4, v1
	v_add_u32_e32 v1, v4, v1
	v_mul_hi_u32 v1, v5, v1
	v_mul_lo_u32 v3, v1, v2
	v_sub_u32_e32 v3, v5, v3
	v_add_u32_e32 v4, 1, v1
	v_cmp_ge_u32_e32 vcc, v3, v2
	s_nop 1
	v_cndmask_b32_e32 v1, v1, v4, vcc
	v_sub_u32_e32 v4, v3, v2
	v_cndmask_b32_e32 v3, v3, v4, vcc
	v_add_u32_e32 v4, 1, v1
	v_cmp_ge_u32_e32 vcc, v3, v2
	v_add_u32_e32 v3, 1, v5
	s_nop 0
	v_cndmask_b32_e32 v1, v1, v4, vcc
	v_mul_lo_u32 v4, v2, v1
	v_add_u32_e32 v2, v4, v2
	v_add_u32_e32 v4, 4, v3
	v_cmp_eq_u32_e32 vcc, v4, v2
	s_cbranch_vccz .Lnopre_0
	buffer_wbl2 sc1

.LBB0_481:
	s_or_b64 exec, exec, s[16:17]
	v_cvt_f32_u32_e32 v4, v2
	s_waitcnt vmcnt(0)
	buffer_inv sc1
	v_readfirstlane_b32 s6, v3
	v_sub_u32_e32 v3, 0, v2
	v_rcp_iflag_f32_e32 v4, v4
	v_add_u32_e32 v5, s6, v1
	v_mul_f32_e32 v4, 0x4f7ffffe, v4
	v_cvt_u32_f32_e32 v4, v4
	v_mul_lo_u32 v1, v3, v4
	v_mul_hi_u32 v1, v4, v1
	v_add_u32_e32 v1, v4, v1
	v_mul_hi_u32 v1, v5, v1
	v_mul_lo_u32 v3, v1, v2
	v_sub_u32_e32 v3, v5, v3
	v_add_u32_e32 v4, 1, v1
	v_cmp_ge_u32_e32 vcc, v3, v2
	s_nop 1
	v_cndmask_b32_e32 v1, v1, v4, vcc
	v_sub_u32_e32 v4, v3, v2
	v_cndmask_b32_e32 v3, v3, v4, vcc
	v_add_u32_e32 v4, 1, v1
	v_cmp_ge_u32_e32 vcc, v3, v2
	v_add_u32_e32 v3, 1, v5
	s_nop 0
	v_cndmask_b32_e32 v1, v1, v4, vcc
	v_mul_lo_u32 v4, v2, v1
	v_add_u32_e32 v2, v4, v2
	v_add_u32_e32 v4, 4, v3
	v_cmp_eq_u32_e32 vcc, v4, v2
	s_cbranch_vccz .Lnopre_5
	buffer_wbl2 sc1

.LBB0_626:
	s_or_b64 exec, exec, s[10:11]
	v_cvt_f32_u32_e32 v4, v2
	s_waitcnt vmcnt(0)
	buffer_inv sc1
	v_readfirstlane_b32 s8, v3
	v_sub_u32_e32 v3, 0, v2
	v_rcp_iflag_f32_e32 v4, v4
	v_add_u32_e32 v5, s8, v1
	v_mul_f32_e32 v4, 0x4f7ffffe, v4
	v_cvt_u32_f32_e32 v4, v4
	v_mul_lo_u32 v1, v3, v4
	v_mul_hi_u32 v1, v4, v1
	v_add_u32_e32 v1, v4, v1
	v_mul_hi_u32 v1, v5, v1
	v_mul_lo_u32 v3, v1, v2
	v_sub_u32_e32 v3, v5, v3
	v_add_u32_e32 v4, 1, v1
	v_cmp_ge_u32_e32 vcc, v3, v2
	s_nop 1
	v_cndmask_b32_e32 v1, v1, v4, vcc
	v_sub_u32_e32 v4, v3, v2
	v_cndmask_b32_e32 v3, v3, v4, vcc
	v_add_u32_e32 v4, 1, v1
	v_cmp_ge_u32_e32 vcc, v3, v2
	v_add_u32_e32 v3, 1, v5
	s_nop 0
	v_cndmask_b32_e32 v1, v1, v4, vcc
	v_mul_lo_u32 v4, v2, v1
	v_add_u32_e32 v2, v4, v2
	v_add_u32_e32 v4, 4, v3
	v_cmp_eq_u32_e32 vcc, v4, v2
	s_cbranch_vccz .Lnopre_7
	buffer_wbl2 sc1

.LBB0_681:
	s_or_b64 exec, exec, s[12:13]
	v_cvt_f32_u32_e32 v4, v2
	s_waitcnt vmcnt(0)
	buffer_inv sc1
	v_readfirstlane_b32 s10, v3
	v_sub_u32_e32 v3, 0, v2
	v_rcp_iflag_f32_e32 v4, v4
	v_add_u32_e32 v5, s10, v1
	v_mul_f32_e32 v4, 0x4f7ffffe, v4
	v_cvt_u32_f32_e32 v4, v4
	v_mul_lo_u32 v1, v3, v4
	v_mul_hi_u32 v1, v4, v1
	v_add_u32_e32 v1, v4, v1
	v_mul_hi_u32 v1, v5, v1
	v_mul_lo_u32 v3, v1, v2
	v_sub_u32_e32 v3, v5, v3
	v_add_u32_e32 v4, 1, v1
	v_cmp_ge_u32_e32 vcc, v3, v2
	s_nop 1
	v_cndmask_b32_e32 v1, v1, v4, vcc
	v_sub_u32_e32 v4, v3, v2
	v_cndmask_b32_e32 v3, v3, v4, vcc
	v_add_u32_e32 v4, 1, v1
	v_cmp_ge_u32_e32 vcc, v3, v2
	v_add_u32_e32 v3, 1, v5
	s_nop 0
	v_cndmask_b32_e32 v1, v1, v4, vcc
	v_mul_lo_u32 v4, v2, v1
	v_add_u32_e32 v2, v4, v2
	v_add_u32_e32 v4, 4, v3
	v_cmp_eq_u32_e32 vcc, v4, v2
	s_cbranch_vccz .Lnopre_8
	buffer_wbl2 sc1

.LBB0_749:
	s_or_b64 exec, exec, s[16:17]
	v_cvt_f32_u32_e32 v4, v2
	s_waitcnt vmcnt(0)
	buffer_inv sc1
	v_readfirstlane_b32 s12, v3
	v_sub_u32_e32 v3, 0, v2
	v_rcp_iflag_f32_e32 v4, v4
	v_add_u32_e32 v5, s12, v1
	v_mul_f32_e32 v4, 0x4f7ffffe, v4
	v_cvt_u32_f32_e32 v4, v4
	v_mul_lo_u32 v1, v3, v4
	v_mul_hi_u32 v1, v4, v1
	v_add_u32_e32 v1, v4, v1
	v_mul_hi_u32 v1, v5, v1
	v_mul_lo_u32 v3, v1, v2
	v_sub_u32_e32 v3, v5, v3
	v_add_u32_e32 v4, 1, v1
	v_cmp_ge_u32_e32 vcc, v3, v2
	s_nop 1
	v_cndmask_b32_e32 v1, v1, v4, vcc
	v_sub_u32_e32 v4, v3, v2
	v_cndmask_b32_e32 v3, v3, v4, vcc
	v_add_u32_e32 v4, 1, v1
	v_cmp_ge_u32_e32 vcc, v3, v2
	v_add_u32_e32 v3, 1, v5
	s_nop 0
	v_cndmask_b32_e32 v1, v1, v4, vcc
	v_mul_lo_u32 v4, v2, v1
	v_add_u32_e32 v2, v4, v2
	v_add_u32_e32 v4, 4, v3
	v_cmp_eq_u32_e32 vcc, v4, v2
	s_cbranch_vccz .Lnopre_9
	buffer_wbl2 sc1
